# P8 rewrite v21: per-image LDS pitches (conflict-free b128/transposed reads), two prefetch sets (distance 2), th0/th1 waves in anti-phase segments with 3 barriers per step
# speedup vs baseline: 1.0178x; 1.0178x over previous
.LBB0_906:
	s_cmp_lt_i32 s90, 9
	s_cselect_b64 s[2:3], -1, 0
	s_and_b64 s[38:39], s[2:3], s[0:1]
	s_andn2_b64 vcc, exec, s[38:39]
	s_cbranch_vccnz .LBB0_998
	s_mov_b64 s[70:71], s[62:63]
	s_mov_b32 s68, s59
	s_mov_b64 s[66:67], s[60:61]
	s_cmpk_gt_i32 s58, 0xff
	v_readfirstlane_b32 s20, v0
	s_cbranch_scc1 .LBB0_997
	v_readlane_b32 s15, v251, 48
	v_readfirstlane_b32 s35, v0
	s_lshr_b32 s35, s35, 6
	s_and_b32 s36, s35, 3
	s_lshr_b32 s37, s35, 2
	s_and_b32 s31, s15, 1
	s_bfe_u32 s73, s15, 0x20001
	s_bfe_u32 s74, s15, 0x20003
	s_lshr_b32 s72, s15, 5
	s_lshl_b32 s33, s72, 8
	s_addk_i32 s33, 0x4000
	s_lshl_b32 s34, s72, 11
	s_addk_i32 s34, 0xff00
	s_movk_i32 s48, 0x1800
	s_movk_i32 s49, 0x400
	s_cmp_eq_u32 s31, 0
	s_cselect_b32 s30, s48, s49
	s_lshl_b32 s48, s73, 8
	s_add_u32 s49, s88, 0xa27d000
	s_addc_u32 s52, s89, 0
	s_cmp_eq_u32 s31, 0
	s_cselect_b32 s16, s96, s49
	s_cselect_b32 s17, s97, s52
	s_add_u32 s16, s16, s48
	s_addc_u32 s17, s17, 0
	s_add_u32 s49, s88, 0xb27d000
	s_addc_u32 s52, s89, 0
	s_add_u32 s53, s96, 0x400
	s_addc_u32 s64, s97, 0
	s_cmp_eq_u32 s31, 0
	s_cselect_b32 s18, s53, s49
	s_cselect_b32 s19, s64, s52
	s_add_u32 s18, s18, s48
	s_addc_u32 s19, s19, 0
	s_lshl_b32 s49, s73, 9
	s_lshl_b32 s52, s74, 7
	s_add_i32 s49, s49, s52
	s_add_i32 s52, s49, 0x800
	s_add_u32 s20, s96, s52
	s_addc_u32 s21, s97, 0
	v_readlane_b32 s28, v251, 34
	v_readlane_b32 s29, v251, 35
	s_lshl_b32 s52, s31, 25
	s_add_i32 s52, s52, s49
	s_add_u32 s28, s28, s52
	s_addc_u32 s29, s29, 0
	s_lshl_b32 s49, s31, 3
	s_add_i32 s49, s49, s72
	s_lshl_b32 s49, s49, 2
	s_add_i32 s49, s49, s73
	s_mul_i32 s49, s49, 0x4800
	s_add_u32 s22, s88, 0x115d000
	s_addc_u32 s23, s89, 0
	s_add_u32 s22, s22, s49
	s_addc_u32 s23, s23, 0
	v_bfe_u32 v94, v0, 4, 2
	v_lshrrev_b32_e32 v95, 2, v186
	v_and_b32_e32 v96, 3, v186
	v_mov_b32_e32 v97, 272
	v_mul_u32_u24_e32 v98, v186, v97
	v_lshl_add_u32 v182, v94, 4, v98
	v_lshl_add_u32 v183, v94, 3, v98
	v_mov_b32_e32 v97, 288
	v_mul_u32_u24_e32 v98, v186, v97
	v_lshl_add_u32 v242, v94, 4, v98
	v_lshl_add_u32 v99, v94, 2, v95
	v_mul_u32_u24_e32 v185, v99, v97
	v_lshl_add_u32 v185, v96, 3, v185
	v_mov_b32_e32 v97, 160
	v_mul_u32_u24_e32 v184, v99, v97
	v_lshl_add_u32 v184, v96, 3, v184
	s_lshl_b32 s49, s36, 5
	v_add_u32_e32 v184, s49, v184
	v_lshlrev_b32_e32 v188, 4, v94
	v_add_u32_e32 v188, 0x16800, v188
	v_lshrrev_b32_e32 v95, 4, v0
	v_mov_b32_e32 v97, 272
	v_mul_u32_u24_e32 v189, v95, v97
	v_lshl_add_u32 v189, v186, 4, v189
	v_mov_b32_e32 v97, 288
	v_mul_u32_u24_e32 v243, v95, v97
	v_lshl_add_u32 v243, v186, 4, v243
	v_lshrrev_b32_e32 v96, 3, v0
	v_and_b32_e32 v98, 7, v0
	v_mov_b32_e32 v97, 160
	v_mul_u32_u24_e32 v190, v96, v97
	v_lshl_add_u32 v190, v98, 4, v190
	v_add_u32_e32 v191, 0x16800, v194
	s_cmp_gt_u32 s35, 1
	s_cselect_b32 s52, 0x200, 0
	v_add_u32_e32 v191, s52, v191
	s_cmp_eq_u32 s31, 0
	s_cselect_b64 vcc, -1, 0
	v_sub_u32_e32 v99, 63, v95
	v_cndmask_b32_e32 v99, v99, v95, vcc
	v_mul_lo_u32 v244, v99, s30
	v_lshl_add_u32 v244, v186, 4, v244
	v_add_u32_e32 v95, 32, v95
	v_sub_u32_e32 v99, 63, v95
	v_cndmask_b32_e32 v99, v99, v95, vcc
	v_mul_lo_u32 v245, v99, s30
	v_lshl_add_u32 v245, v186, 4, v245
	v_sub_u32_e32 v99, 63, v96
	v_cndmask_b32_e32 v99, v99, v96, vcc
	v_mov_b32_e32 v97, 0x1800
	v_mul_lo_u32 v246, v99, v97
	v_lshl_add_u32 v246, v98, 4, v246
	v_sub_u32_e32 v99, 15, v186
	v_cndmask_b32_e32 v99, v99, v186, vcc
	v_lshlrev_b32_e32 v247, 11, v99
	v_lshl_add_u32 v247, v94, 3, v247
	v_add_u32_e32 v247, s49, v247
	v_lshlrev_b32_e32 v95, 2, v94
	v_cmp_gt_u32_e64 s[40:41], v95, v186
	v_add_u32_e32 v96, 1, v95
	v_cmp_gt_u32_e64 s[42:43], v96, v186
	v_add_u32_e32 v96, 2, v95
	v_cmp_gt_u32_e64 s[44:45], v96, v186
	v_add_u32_e32 v96, 3, v95
	v_cmp_gt_u32_e64 s[46:47], v96, v186
	v_mov_b32_e32 v2, 0
	v_mov_b32_e32 v3, 0
	v_mov_b32_e32 v4, 0
	v_mov_b32_e32 v5, 0
	v_mov_b32_e32 v6, 0
	v_mov_b32_e32 v7, 0
	v_mov_b32_e32 v8, 0
	v_mov_b32_e32 v9, 0
	v_mov_b32_e32 v10, 0
	v_mov_b32_e32 v11, 0
	v_mov_b32_e32 v12, 0
	v_mov_b32_e32 v13, 0
	v_mov_b32_e32 v14, 0
	v_mov_b32_e32 v15, 0
	v_mov_b32_e32 v16, 0
	v_mov_b32_e32 v17, 0
	v_mov_b32_e32 v18, 0
	v_mov_b32_e32 v19, 0
	v_mov_b32_e32 v20, 0
	v_mov_b32_e32 v21, 0
	v_mov_b32_e32 v22, 0
	v_mov_b32_e32 v23, 0
	v_mov_b32_e32 v24, 0
	v_mov_b32_e32 v25, 0
	v_mov_b32_e32 v26, 0
	v_mov_b32_e32 v27, 0
	v_mov_b32_e32 v28, 0
	v_mov_b32_e32 v29, 0
	v_mov_b32_e32 v30, 0
	v_mov_b32_e32 v31, 0
	v_mov_b32_e32 v32, 0
	v_mov_b32_e32 v33, 0
	v_add_u32_e32 v182, 0xb400, v182
	v_add_u32_e32 v183, 0xb400, v183
	v_add_u32_e32 v184, 0xb400, v184
	v_add_u32_e32 v185, 0xb400, v185
	v_add_u32_e32 v242, 0xb400, v242
	v_add_u32_e32 v188, 0x200, v188
	s_mov_b32 s64, 0
	s_min_u32 s65, s64, 35
	s_sub_i32 s48, 3, s65
	s_sub_i32 s49, 39, s65
	s_cmp_lt_u32 s65, 4
	s_cselect_b32 s48, s48, s49
	s_cmp_eq_u32 s31, 0
	s_cselect_b32 s54, s65, s48
	s_lshl_b32 s48, s54, 6
	s_add_i32 s49, s33, s48
	s_add_i32 s48, s34, s48
	s_cmp_lt_u32 s54, 4
	s_cselect_b32 s55, s49, s48
	s_mul_i32 s48, s55, s30
	s_add_u32 s0, s16, s48
	s_addc_u32 s1, s17, 0
	s_add_u32 s2, s18, s48
	s_addc_u32 s3, s19, 0
	s_mul_i32 s48, s55, 0x1800
	s_add_u32 s4, s20, s48
	s_addc_u32 s5, s21, 0
	s_lshl_b32 s48, s54, 9
	s_add_u32 s6, s22, s48
	s_addc_u32 s7, s23, 0
	global_load_dwordx4 v[224:227], v244, s[2:3]
	global_load_dwordx4 v[228:231], v245, s[2:3]
	global_load_dwordx4 v[232:235], v246, s[4:5]
	global_load_dwordx4 v[216:219], v244, s[0:1]
	global_load_dwordx4 v[220:223], v245, s[0:1]
	global_load_dword v236, v194, s[6:7]
	s_mov_b32 s64, 1
	s_min_u32 s65, s64, 35
	s_sub_i32 s48, 3, s65
	s_sub_i32 s49, 39, s65
	s_cmp_lt_u32 s65, 4
	s_cselect_b32 s48, s48, s49
	s_cmp_eq_u32 s31, 0
	s_cselect_b32 s54, s65, s48
	s_lshl_b32 s48, s54, 6
	s_add_i32 s49, s33, s48
	s_add_i32 s48, s34, s48
	s_cmp_lt_u32 s54, 4
	s_cselect_b32 s55, s49, s48
	s_mul_i32 s48, s55, s30
	s_add_u32 s0, s16, s48
	s_addc_u32 s1, s17, 0
	s_add_u32 s2, s18, s48
	s_addc_u32 s3, s19, 0
	s_mul_i32 s48, s55, 0x1800
	s_add_u32 s4, s20, s48
	s_addc_u32 s5, s21, 0
	s_lshl_b32 s48, s54, 9
	s_add_u32 s6, s22, s48
	s_addc_u32 s7, s23, 0
	global_load_dwordx4 v[142:145], v244, s[2:3]
	global_load_dwordx4 v[146:149], v245, s[2:3]
	global_load_dwordx4 v[238:241], v246, s[4:5]
	global_load_dwordx4 v[134:137], v244, s[0:1]
	global_load_dwordx4 v[138:141], v245, s[0:1]
	global_load_dword v237, v194, s[6:7]
	s_waitcnt vmcnt(6)
	ds_write_b128 v243, v[224:227] offset:17408
	ds_write_b128 v243, v[228:231] offset:26624
	ds_write_b128 v190, v[232:235] offset:35840
	ds_write_b128 v189, v[216:219]
	ds_write_b128 v189, v[220:223] offset:8704
	ds_write_b32 v191, v236
	s_mov_b32 s64, 2
	s_min_u32 s65, s64, 35
	s_sub_i32 s48, 3, s65
	s_sub_i32 s49, 39, s65
	s_cmp_lt_u32 s65, 4
	s_cselect_b32 s48, s48, s49
	s_cmp_eq_u32 s31, 0
	s_cselect_b32 s54, s65, s48
	s_lshl_b32 s48, s54, 6
	s_add_i32 s49, s33, s48
	s_add_i32 s48, s34, s48
	s_cmp_lt_u32 s54, 4
	s_cselect_b32 s55, s49, s48
	s_mul_i32 s48, s55, s30
	s_add_u32 s0, s16, s48
	s_addc_u32 s1, s17, 0
	s_add_u32 s2, s18, s48
	s_addc_u32 s3, s19, 0
	s_mul_i32 s48, s55, 0x1800
	s_add_u32 s4, s20, s48
	s_addc_u32 s5, s21, 0
	s_lshl_b32 s48, s54, 9
	s_add_u32 s6, s22, s48
	s_addc_u32 s7, s23, 0
	global_load_dwordx4 v[224:227], v244, s[2:3]
	global_load_dwordx4 v[228:231], v245, s[2:3]
	global_load_dwordx4 v[232:235], v246, s[4:5]
	global_load_dwordx4 v[216:219], v244, s[0:1]
	global_load_dwordx4 v[220:223], v245, s[0:1]
	global_load_dword v236, v194, s[6:7]
	s_mov_b32 s12, 0
	s_waitcnt lgkmcnt(0)
	s_barrier
.Lp8_step:
	v_add_u32_e32 v182, 0xffff4c00, v182
	v_add_u32_e32 v183, 0xffff4c00, v183
	v_add_u32_e32 v184, 0xffff4c00, v184
	v_add_u32_e32 v185, 0xffff4c00, v185
	v_add_u32_e32 v242, 0xffff4c00, v242
	v_add_u32_e32 v189, 0xb400, v189
	v_add_u32_e32 v243, 0xb400, v243
	v_add_u32_e32 v190, 0xb400, v190
	v_add_u32_e32 v188, 0xfffffe00, v188
	v_add_u32_e32 v191, 0x200, v191
	s_cmp_lt_u32 s12, 4
	s_nop 0
	s_cbranch_scc0 .Lp8_lat_0
	ds_read_b64_tr_b16 v[126:127], v184 offset:35840
	ds_read_b64_tr_b16 v[128:129], v184 offset:38400
	ds_read_b64_tr_b16 v[130:131], v184 offset:40960
	ds_read_b64_tr_b16 v[132:133], v184 offset:43520
	ds_read_b64_tr_b16 v[62:63], v185 offset:17408
	ds_read_b64_tr_b16 v[64:65], v185 offset:22016
	ds_read_b64_tr_b16 v[66:67], v185 offset:26624
	ds_read_b64_tr_b16 v[68:69], v185 offset:31232
	ds_read_b64_tr_b16 v[70:71], v185 offset:17440
	ds_read_b64_tr_b16 v[72:73], v185 offset:22048
	ds_read_b64_tr_b16 v[74:75], v185 offset:26656
	ds_read_b64_tr_b16 v[76:77], v185 offset:31264
	ds_read_b64_tr_b16 v[78:79], v185 offset:17472
	ds_read_b64_tr_b16 v[80:81], v185 offset:22080
	ds_read_b64_tr_b16 v[82:83], v185 offset:26688
	ds_read_b64_tr_b16 v[84:85], v185 offset:31296
	ds_read_b64_tr_b16 v[86:87], v185 offset:17504
	ds_read_b64_tr_b16 v[88:89], v185 offset:22112
	ds_read_b64_tr_b16 v[90:91], v185 offset:26720
	ds_read_b64_tr_b16 v[92:93], v185 offset:31328
	ds_read_b64_tr_b16 v[94:95], v185 offset:17536
	ds_read_b64_tr_b16 v[96:97], v185 offset:22144
	ds_read_b64_tr_b16 v[98:99], v185 offset:26752
	ds_read_b64_tr_b16 v[100:101], v185 offset:31360
	ds_read_b64_tr_b16 v[102:103], v185 offset:17568
	ds_read_b64_tr_b16 v[104:105], v185 offset:22176
	ds_read_b64_tr_b16 v[106:107], v185 offset:26784
	ds_read_b64_tr_b16 v[108:109], v185 offset:31392
	ds_read_b64_tr_b16 v[110:111], v185 offset:17600
	ds_read_b64_tr_b16 v[112:113], v185 offset:22208
	ds_read_b64_tr_b16 v[114:115], v185 offset:26816
	ds_read_b64_tr_b16 v[116:117], v185 offset:31424
	ds_read_b64_tr_b16 v[118:119], v185 offset:17632
	ds_read_b64_tr_b16 v[120:121], v185 offset:22240
	ds_read_b64_tr_b16 v[122:123], v185 offset:26848
	ds_read_b64_tr_b16 v[124:125], v185 offset:31456
	ds_read_b128 v[166:169], v188 offset:0
	ds_read_b128 v[170:173], v188 offset:64
	ds_read_b128 v[174:177], v188 offset:128
	ds_read_b128 v[178:181], v188 offset:192
	ds_read_b128 v[200:203], v188 offset:256
	ds_read_b128 v[204:207], v188 offset:320
	ds_read_b128 v[208:211], v188 offset:384
	ds_read_b128 v[212:215], v188 offset:448
	s_waitcnt vmcnt(6)
	ds_write_b128 v243, v[142:145] offset:17408
	ds_write_b128 v243, v[146:149] offset:26624
	ds_write_b128 v190, v[238:241] offset:35840
	ds_write_b128 v189, v[134:137]
	ds_write_b128 v189, v[138:141] offset:8704
	ds_write_b32 v191, v237
	s_add_i32 s64, s12, 3
	s_min_u32 s65, s64, 35
	s_sub_i32 s48, 3, s65
	s_sub_i32 s49, 39, s65
	s_cmp_lt_u32 s65, 4
	s_cselect_b32 s48, s48, s49
	s_cmp_eq_u32 s31, 0
	s_cselect_b32 s54, s65, s48
	s_lshl_b32 s48, s54, 6
	s_add_i32 s49, s33, s48
	s_add_i32 s48, s34, s48
	s_cmp_lt_u32 s54, 4
	s_cselect_b32 s55, s49, s48
	s_mul_i32 s48, s55, s30
	s_add_u32 s0, s16, s48
	s_addc_u32 s1, s17, 0
	s_add_u32 s2, s18, s48
	s_addc_u32 s3, s19, 0
	s_mul_i32 s48, s55, 0x1800
	s_add_u32 s4, s20, s48
	s_addc_u32 s5, s21, 0
	s_lshl_b32 s48, s54, 9
	s_add_u32 s6, s22, s48
	s_addc_u32 s7, s23, 0
	global_load_dwordx4 v[142:145], v244, s[2:3]
	global_load_dwordx4 v[146:149], v245, s[2:3]
	global_load_dwordx4 v[238:241], v246, s[4:5]
	global_load_dwordx4 v[134:137], v244, s[0:1]
	global_load_dwordx4 v[138:141], v245, s[0:1]
	global_load_dword v237, v194, s[6:7]
	s_waitcnt lgkmcnt(15)
	v_mfma_f32_16x16x32_bf16 v[2:5], v[62:65], v[126:129], v[2:5]
	v_mfma_f32_16x16x32_bf16 v[2:5], v[66:69], v[130:133], v[2:5]
	v_mfma_f32_16x16x32_bf16 v[6:9], v[70:73], v[126:129], v[6:9]
	v_mfma_f32_16x16x32_bf16 v[6:9], v[74:77], v[130:133], v[6:9]
	v_mfma_f32_16x16x32_bf16 v[10:13], v[78:81], v[126:129], v[10:13]
	v_mfma_f32_16x16x32_bf16 v[10:13], v[82:85], v[130:133], v[10:13]
	v_mfma_f32_16x16x32_bf16 v[14:17], v[86:89], v[126:129], v[14:17]
	v_mfma_f32_16x16x32_bf16 v[14:17], v[90:93], v[130:133], v[14:17]
	s_waitcnt lgkmcnt(14)
	v_mfma_f32_16x16x32_bf16 v[18:21], v[94:97], v[126:129], v[18:21]
	v_mfma_f32_16x16x32_bf16 v[18:21], v[98:101], v[130:133], v[18:21]
	v_mfma_f32_16x16x32_bf16 v[22:25], v[102:105], v[126:129], v[22:25]
	v_mfma_f32_16x16x32_bf16 v[22:25], v[106:109], v[130:133], v[22:25]
	v_mfma_f32_16x16x32_bf16 v[26:29], v[110:113], v[126:129], v[26:29]
	v_mfma_f32_16x16x32_bf16 v[26:29], v[114:117], v[130:133], v[26:29]
	v_mfma_f32_16x16x32_bf16 v[30:33], v[118:121], v[126:129], v[30:33]
	v_mfma_f32_16x16x32_bf16 v[30:33], v[122:125], v[130:133], v[30:33]
	s_waitcnt lgkmcnt(0)
	v_pk_mul_f32 v[2:3], v[2:3], v[166:167]
	v_pk_mul_f32 v[4:5], v[4:5], v[168:169]
	v_pk_mul_f32 v[6:7], v[6:7], v[170:171]
	v_pk_mul_f32 v[8:9], v[8:9], v[172:173]
	v_pk_mul_f32 v[10:11], v[10:11], v[174:175]
	v_pk_mul_f32 v[12:13], v[12:13], v[176:177]
	v_pk_mul_f32 v[14:15], v[14:15], v[178:179]
	v_pk_mul_f32 v[16:17], v[16:17], v[180:181]
	v_pk_mul_f32 v[18:19], v[18:19], v[200:201]
	v_pk_mul_f32 v[20:21], v[20:21], v[202:203]
	v_pk_mul_f32 v[22:23], v[22:23], v[204:205]
	v_pk_mul_f32 v[24:25], v[24:25], v[206:207]
	v_pk_mul_f32 v[26:27], v[26:27], v[208:209]
	v_pk_mul_f32 v[28:29], v[28:29], v[210:211]
	v_pk_mul_f32 v[30:31], v[30:31], v[212:213]
	v_pk_mul_f32 v[32:33], v[32:33], v[214:215]
	s_nop 1
	s_barrier
	s_branch .Lp8_next_0
.Lp8_lat_0:
	s_cmp_eq_u32 s37, 0
	s_cbranch_scc0 .Lp8_lat1_0
	s_sub_i32 s48, 3, s12
	s_sub_i32 s49, 39, s12
	s_cmp_lt_u32 s12, 4
	s_cselect_b32 s48, s48, s49
	s_cmp_eq_u32 s31, 0
	s_cselect_b32 s54, s12, s48
	s_lshl_b32 s48, s54, 6
	s_add_i32 s49, s33, s48
	s_add_i32 s48, s34, s48
	s_cmp_lt_u32 s54, 4
	s_cselect_b32 s55, s49, s48
	s_add_i32 s48, s55, 0
	s_add_i32 s49, s55, 48
	s_cmp_eq_u32 s31, 0
	s_cselect_b32 s48, s48, s49
	s_lshl_b32 s48, s48, 11
	s_add_u32 s8, s28, s48
	s_addc_u32 s9, s29, 0
	s_add_i32 s48, s55, 48
	s_add_i32 s49, s55, 0
	s_cmp_eq_u32 s31, 0
	s_cselect_b32 s48, s48, s49
	s_lshl_b32 s48, s48, 11
	s_add_u32 s10, s28, s48
	s_addc_u32 s11, s29, 0
	v_cvt_pk_bf16_f32 v150, v2, v3
	v_cvt_pk_bf16_f32 v151, v4, v5
	v_cvt_pk_bf16_f32 v152, v6, v7
	v_cvt_pk_bf16_f32 v153, v8, v9
	v_cvt_pk_bf16_f32 v154, v10, v11
	v_cvt_pk_bf16_f32 v155, v12, v13
	v_cvt_pk_bf16_f32 v156, v14, v15
	v_cvt_pk_bf16_f32 v157, v16, v17
	v_cvt_pk_bf16_f32 v158, v18, v19
	v_cvt_pk_bf16_f32 v159, v20, v21
	v_cvt_pk_bf16_f32 v160, v22, v23
	v_cvt_pk_bf16_f32 v161, v24, v25
	v_cvt_pk_bf16_f32 v162, v26, v27
	v_cvt_pk_bf16_f32 v163, v28, v29
	v_cvt_pk_bf16_f32 v164, v30, v31
	v_cvt_pk_bf16_f32 v165, v32, v33
	ds_read_b64_tr_b16 v[126:127], v184 offset:35840
	ds_read_b64_tr_b16 v[128:129], v184 offset:38400
	ds_read_b64_tr_b16 v[130:131], v184 offset:40960
	ds_read_b64_tr_b16 v[132:133], v184 offset:43520
	ds_read_b64_tr_b16 v[62:63], v185 offset:17408
	ds_read_b64_tr_b16 v[64:65], v185 offset:22016
	ds_read_b64_tr_b16 v[66:67], v185 offset:26624
	ds_read_b64_tr_b16 v[68:69], v185 offset:31232
	ds_read_b64_tr_b16 v[70:71], v185 offset:17440
	ds_read_b64_tr_b16 v[72:73], v185 offset:22048
	ds_read_b64_tr_b16 v[74:75], v185 offset:26656
	ds_read_b64_tr_b16 v[76:77], v185 offset:31264
	ds_read_b64_tr_b16 v[78:79], v185 offset:17472
	ds_read_b64_tr_b16 v[80:81], v185 offset:22080
	ds_read_b64_tr_b16 v[82:83], v185 offset:26688
	ds_read_b64_tr_b16 v[84:85], v185 offset:31296
	ds_read_b64_tr_b16 v[86:87], v185 offset:17504
	ds_read_b64_tr_b16 v[88:89], v185 offset:22112
	ds_read_b64_tr_b16 v[90:91], v185 offset:26720
	ds_read_b64_tr_b16 v[92:93], v185 offset:31328
	ds_read_b64 v[94:95], v183 offset:0
	ds_read_b64 v[96:97], v183 offset:32
	ds_read_b64 v[98:99], v183 offset:64
	ds_read_b64 v[100:101], v183 offset:96
	ds_read_b64 v[102:103], v183 offset:128
	ds_read_b64 v[104:105], v183 offset:160
	ds_read_b64 v[106:107], v183 offset:192
	ds_read_b64 v[108:109], v183 offset:224
	ds_read_b64 v[110:111], v183 offset:13056
	ds_read_b64 v[112:113], v183 offset:13088
	ds_read_b64 v[114:115], v183 offset:13120
	ds_read_b64 v[116:117], v183 offset:13152
	ds_read_b64 v[118:119], v183 offset:13184
	ds_read_b64 v[120:121], v183 offset:13216
	ds_read_b64 v[122:123], v183 offset:13248
	ds_read_b64 v[124:125], v183 offset:13280
	s_waitcnt lgkmcnt(15)
	v_mfma_f32_16x16x32_bf16 v[2:5], v[62:65], v[126:129], v[2:5]
	v_mfma_f32_16x16x32_bf16 v[2:5], v[66:69], v[130:133], v[2:5]
	v_mfma_f32_16x16x32_bf16 v[6:9], v[70:73], v[126:129], v[6:9]
	v_mfma_f32_16x16x32_bf16 v[6:9], v[74:77], v[130:133], v[6:9]
	v_mfma_f32_16x16x32_bf16 v[10:13], v[78:81], v[126:129], v[10:13]
	v_mfma_f32_16x16x32_bf16 v[10:13], v[82:85], v[130:133], v[10:13]
	v_mfma_f32_16x16x32_bf16 v[14:17], v[86:89], v[126:129], v[14:17]
	v_mfma_f32_16x16x32_bf16 v[14:17], v[90:93], v[130:133], v[14:17]
	s_waitcnt lgkmcnt(0)
	v_mfma_f32_16x16x32_bf16 v[34:37], v[150:153], v[94:97], 0
	v_mfma_f32_16x16x32_bf16 v[38:41], v[150:153], v[110:113], 0
	v_mfma_f32_16x16x32_bf16 v[34:37], v[154:157], v[98:101], v[34:37]
	v_mfma_f32_16x16x32_bf16 v[38:41], v[154:157], v[114:117], v[38:41]
	v_mfma_f32_16x16x32_bf16 v[34:37], v[158:161], v[102:105], v[34:37]
	v_mfma_f32_16x16x32_bf16 v[38:41], v[158:161], v[118:121], v[38:41]
	v_mfma_f32_16x16x32_bf16 v[34:37], v[162:165], v[106:109], v[34:37]
	v_mfma_f32_16x16x32_bf16 v[38:41], v[162:165], v[122:125], v[38:41]
	s_nop 7
	s_barrier
	ds_read_b128 v[62:65], v182 offset:0
	ds_read_b128 v[66:69], v182 offset:64
	ds_read_b128 v[70:73], v182 offset:128
	ds_read_b128 v[74:77], v182 offset:192
	ds_read_b128 v[78:81], v182 offset:13056
	ds_read_b128 v[82:85], v182 offset:13120
	ds_read_b128 v[86:89], v182 offset:13184
	ds_read_b128 v[90:93], v182 offset:13248
	ds_read_b128 v[166:169], v242 offset:17408
	ds_read_b128 v[170:173], v242 offset:17472
	ds_read_b128 v[174:177], v242 offset:17536
	ds_read_b128 v[178:181], v242 offset:17600
	ds_read_b128 v[200:203], v242 offset:22016
	ds_read_b128 v[204:207], v242 offset:22080
	ds_read_b128 v[208:211], v242 offset:22144
	ds_read_b128 v[212:215], v242 offset:22208
	ds_read_b128 v[94:97], v242 offset:26624
	ds_read_b128 v[98:101], v242 offset:26688
	ds_read_b128 v[102:105], v242 offset:26752
	ds_read_b128 v[106:109], v242 offset:26816
	ds_read_b128 v[110:113], v242 offset:31232
	ds_read_b128 v[114:117], v242 offset:31296
	ds_read_b128 v[118:121], v242 offset:31360
	ds_read_b128 v[122:125], v242 offset:31424
	s_cmp_gt_u32 s12, 5
	s_cbranch_scc1 .Lp8_w10_2
	s_waitcnt vmcnt(6)
	s_branch .Lp8_wd_2
.Lp8_w10_2:
	s_waitcnt vmcnt(10)
.Lp8_wd_2:
	ds_write_b128 v243, v[142:145] offset:17408
	ds_write_b128 v243, v[146:149] offset:26624
	ds_write_b128 v190, v[238:241] offset:35840
	ds_write_b128 v189, v[134:137]
	ds_write_b128 v189, v[138:141] offset:8704
	ds_write_b32 v191, v237
	s_add_i32 s64, s12, 3
	s_min_u32 s65, s64, 35
	s_sub_i32 s48, 3, s65
	s_sub_i32 s49, 39, s65
	s_cmp_lt_u32 s65, 4
	s_cselect_b32 s48, s48, s49
	s_cmp_eq_u32 s31, 0
	s_cselect_b32 s54, s65, s48
	s_lshl_b32 s48, s54, 6
	s_add_i32 s49, s33, s48
	s_add_i32 s48, s34, s48
	s_cmp_lt_u32 s54, 4
	s_cselect_b32 s55, s49, s48
	s_mul_i32 s48, s55, s30
	s_add_u32 s0, s16, s48
	s_addc_u32 s1, s17, 0
	s_add_u32 s2, s18, s48
	s_addc_u32 s3, s19, 0
	s_mul_i32 s48, s55, 0x1800
	s_add_u32 s4, s20, s48
	s_addc_u32 s5, s21, 0
	s_lshl_b32 s48, s54, 9
	s_add_u32 s6, s22, s48
	s_addc_u32 s7, s23, 0
	global_load_dwordx4 v[142:145], v244, s[2:3]
	global_load_dwordx4 v[146:149], v245, s[2:3]
	global_load_dwordx4 v[238:241], v246, s[4:5]
	global_load_dwordx4 v[134:137], v244, s[0:1]
	global_load_dwordx4 v[138:141], v245, s[0:1]
	global_load_dword v237, v194, s[6:7]
	s_waitcnt lgkmcnt(15)
	v_mfma_f32_16x16x32_bf16 v[42:45], v[166:169], v[62:65], 0
	v_mfma_f32_16x16x32_bf16 v[46:49], v[166:169], v[78:81], 0
	v_mfma_f32_16x16x32_bf16 v[42:45], v[170:173], v[66:69], v[42:45]
	v_mfma_f32_16x16x32_bf16 v[46:49], v[170:173], v[82:85], v[46:49]
	v_mfma_f32_16x16x32_bf16 v[42:45], v[174:177], v[70:73], v[42:45]
	v_mfma_f32_16x16x32_bf16 v[46:49], v[174:177], v[86:89], v[46:49]
	v_mfma_f32_16x16x32_bf16 v[42:45], v[178:181], v[74:77], v[42:45]
	v_mfma_f32_16x16x32_bf16 v[46:49], v[178:181], v[90:93], v[46:49]
	s_waitcnt lgkmcnt(14)
	v_mfma_f32_16x16x32_bf16 v[50:53], v[200:203], v[78:81], 0
	v_mfma_f32_16x16x32_bf16 v[50:53], v[204:207], v[82:85], v[50:53]
	v_mfma_f32_16x16x32_bf16 v[50:53], v[208:211], v[86:89], v[50:53]
	v_mfma_f32_16x16x32_bf16 v[50:53], v[212:215], v[90:93], v[50:53]
	s_waitcnt lgkmcnt(10)
	v_mfma_f32_16x16x32_bf16 v[54:57], v[94:97], v[78:81], 0
	v_mfma_f32_16x16x32_bf16 v[54:57], v[98:101], v[82:85], v[54:57]
	v_mfma_f32_16x16x32_bf16 v[54:57], v[102:105], v[86:89], v[54:57]
	v_mfma_f32_16x16x32_bf16 v[54:57], v[106:109], v[90:93], v[54:57]
	s_waitcnt lgkmcnt(6)
	v_mfma_f32_16x16x32_bf16 v[58:61], v[110:113], v[78:81], 0
	v_mfma_f32_16x16x32_bf16 v[58:61], v[114:117], v[82:85], v[58:61]
	v_mfma_f32_16x16x32_bf16 v[58:61], v[118:121], v[86:89], v[58:61]
	v_mfma_f32_16x16x32_bf16 v[58:61], v[122:125], v[90:93], v[58:61]
	s_nop 7
	s_barrier
	ds_read_b64_tr_b16 v[62:63], v185 offset:17536
	ds_read_b64_tr_b16 v[64:65], v185 offset:22144
	ds_read_b64_tr_b16 v[66:67], v185 offset:26752
	ds_read_b64_tr_b16 v[68:69], v185 offset:31360
	ds_read_b64_tr_b16 v[70:71], v185 offset:17568
	ds_read_b64_tr_b16 v[72:73], v185 offset:22176
	ds_read_b64_tr_b16 v[74:75], v185 offset:26784
	ds_read_b64_tr_b16 v[76:77], v185 offset:31392
	ds_read_b64_tr_b16 v[78:79], v185 offset:17600
	ds_read_b64_tr_b16 v[80:81], v185 offset:22208
	ds_read_b64_tr_b16 v[82:83], v185 offset:26816
	ds_read_b64_tr_b16 v[84:85], v185 offset:31424
	ds_read_b64_tr_b16 v[86:87], v185 offset:17632
	ds_read_b64_tr_b16 v[88:89], v185 offset:22240
	ds_read_b64_tr_b16 v[90:91], v185 offset:26848
	ds_read_b64_tr_b16 v[92:93], v185 offset:31456
	ds_read_b128 v[166:169], v188 offset:0
	ds_read_b128 v[170:173], v188 offset:64
	ds_read_b128 v[174:177], v188 offset:128
	ds_read_b128 v[178:181], v188 offset:192
	ds_read_b128 v[200:203], v188 offset:256
	ds_read_b128 v[204:207], v188 offset:320
	ds_read_b128 v[208:211], v188 offset:384
	ds_read_b128 v[212:215], v188 offset:448
	s_waitcnt lgkmcnt(8)
	v_mfma_f32_16x16x32_bf16 v[18:21], v[62:65], v[126:129], v[18:21]
	v_mfma_f32_16x16x32_bf16 v[18:21], v[66:69], v[130:133], v[18:21]
	v_mfma_f32_16x16x32_bf16 v[22:25], v[70:73], v[126:129], v[22:25]
	v_mfma_f32_16x16x32_bf16 v[22:25], v[74:77], v[130:133], v[22:25]
	v_mfma_f32_16x16x32_bf16 v[26:29], v[78:81], v[126:129], v[26:29]
	v_mfma_f32_16x16x32_bf16 v[26:29], v[82:85], v[130:133], v[26:29]
	v_mfma_f32_16x16x32_bf16 v[30:33], v[86:89], v[126:129], v[30:33]
	v_mfma_f32_16x16x32_bf16 v[30:33], v[90:93], v[130:133], v[30:33]
	v_cndmask_b32_e64 v42, v42, 0, s[40:41]
	v_cndmask_b32_e64 v43, v43, 0, s[42:43]
	v_cndmask_b32_e64 v44, v44, 0, s[44:45]
	v_cndmask_b32_e64 v45, v45, 0, s[46:47]
	v_cndmask_b32_e64 v58, v58, 0, s[40:41]
	v_cndmask_b32_e64 v59, v59, 0, s[42:43]
	v_cndmask_b32_e64 v60, v60, 0, s[44:45]
	v_cndmask_b32_e64 v61, v61, 0, s[46:47]
	v_cvt_pk_bf16_f32 v150, v42, v43
	v_cvt_pk_bf16_f32 v151, v44, v45
	v_mov_b32_e32 v152, 0
	v_mov_b32_e32 v153, 0
	v_cvt_pk_bf16_f32 v154, v46, v47
	v_cvt_pk_bf16_f32 v155, v48, v49
	v_cvt_pk_bf16_f32 v156, v50, v51
	v_cvt_pk_bf16_f32 v157, v52, v53
	v_cvt_pk_bf16_f32 v158, v54, v55
	v_cvt_pk_bf16_f32 v159, v56, v57
	v_cvt_pk_bf16_f32 v160, v58, v59
	v_cvt_pk_bf16_f32 v161, v60, v61
	v_mfma_f32_16x16x32_bf16 v[34:37], v[126:129], v[150:153], v[34:37]
	v_mfma_f32_16x16x32_bf16 v[38:41], v[126:129], v[154:157], v[38:41]
	v_mfma_f32_16x16x32_bf16 v[38:41], v[130:133], v[158:161], v[38:41]
	s_waitcnt lgkmcnt(0)
	v_pk_mul_f32 v[2:3], v[2:3], v[166:167]
	v_pk_mul_f32 v[4:5], v[4:5], v[168:169]
	v_pk_mul_f32 v[6:7], v[6:7], v[170:171]
	v_pk_mul_f32 v[8:9], v[8:9], v[172:173]
	v_pk_mul_f32 v[10:11], v[10:11], v[174:175]
	v_pk_mul_f32 v[12:13], v[12:13], v[176:177]
	v_pk_mul_f32 v[14:15], v[14:15], v[178:179]
	v_pk_mul_f32 v[16:17], v[16:17], v[180:181]
	v_pk_mul_f32 v[18:19], v[18:19], v[200:201]
	v_pk_mul_f32 v[20:21], v[20:21], v[202:203]
	v_pk_mul_f32 v[22:23], v[22:23], v[204:205]
	v_pk_mul_f32 v[24:25], v[24:25], v[206:207]
	v_pk_mul_f32 v[26:27], v[26:27], v[208:209]
	v_pk_mul_f32 v[28:29], v[28:29], v[210:211]
	v_pk_mul_f32 v[30:31], v[30:31], v[212:213]
	v_pk_mul_f32 v[32:33], v[32:33], v[214:215]
	v_cvt_pk_bf16_f32 v42, v34, v35
	v_cvt_pk_bf16_f32 v43, v36, v37
	global_store_dwordx2 v247, v[42:43], s[8:9]
	v_cvt_pk_bf16_f32 v44, v38, v39
	v_cvt_pk_bf16_f32 v45, v40, v41
	global_store_dwordx2 v247, v[44:45], s[10:11]
	s_nop 0
	s_barrier
	s_branch .Lp8_next_0
.Lp8_lat1_0:
	s_cmp_eq_u32 s12, 4
	s_cbranch_scc1 .Lp8_first_3
	s_waitcnt lgkmcnt(8)
	v_mfma_f32_16x16x32_bf16 v[18:21], v[62:65], v[126:129], v[18:21]
	v_mfma_f32_16x16x32_bf16 v[18:21], v[66:69], v[130:133], v[18:21]
	v_mfma_f32_16x16x32_bf16 v[22:25], v[70:73], v[126:129], v[22:25]
	v_mfma_f32_16x16x32_bf16 v[22:25], v[74:77], v[130:133], v[22:25]
	v_mfma_f32_16x16x32_bf16 v[26:29], v[78:81], v[126:129], v[26:29]
	v_mfma_f32_16x16x32_bf16 v[26:29], v[82:85], v[130:133], v[26:29]
	v_mfma_f32_16x16x32_bf16 v[30:33], v[86:89], v[126:129], v[30:33]
	v_mfma_f32_16x16x32_bf16 v[30:33], v[90:93], v[130:133], v[30:33]
	v_cndmask_b32_e64 v46, v46, 0, s[40:41]
	v_cndmask_b32_e64 v47, v47, 0, s[42:43]
	v_cndmask_b32_e64 v48, v48, 0, s[44:45]
	v_cndmask_b32_e64 v49, v49, 0, s[46:47]
	v_cndmask_b32_e64 v58, v58, 0, s[40:41]
	v_cndmask_b32_e64 v59, v59, 0, s[42:43]
	v_cndmask_b32_e64 v60, v60, 0, s[44:45]
	v_cndmask_b32_e64 v61, v61, 0, s[46:47]
	v_cvt_pk_bf16_f32 v150, v42, v43
	v_cvt_pk_bf16_f32 v151, v44, v45
	v_cvt_pk_bf16_f32 v152, v46, v47
	v_cvt_pk_bf16_f32 v153, v48, v49
	v_cvt_pk_bf16_f32 v154, v50, v51
	v_cvt_pk_bf16_f32 v155, v52, v53
	v_cvt_pk_bf16_f32 v156, v54, v55
	v_cvt_pk_bf16_f32 v157, v56, v57
	v_cvt_pk_bf16_f32 v158, v58, v59
	v_cvt_pk_bf16_f32 v159, v60, v61
	v_mov_b32_e32 v160, 0
	v_mov_b32_e32 v161, 0
	v_mfma_f32_16x16x32_bf16 v[34:37], v[126:129], v[150:153], v[34:37]
	v_mfma_f32_16x16x32_bf16 v[38:41], v[126:129], v[154:157], v[38:41]
	v_mfma_f32_16x16x32_bf16 v[38:41], v[130:133], v[158:161], v[38:41]
	s_waitcnt lgkmcnt(0)
	v_pk_mul_f32 v[2:3], v[2:3], v[166:167]
	v_pk_mul_f32 v[4:5], v[4:5], v[168:169]
	v_pk_mul_f32 v[6:7], v[6:7], v[170:171]
	v_pk_mul_f32 v[8:9], v[8:9], v[172:173]
	v_pk_mul_f32 v[10:11], v[10:11], v[174:175]
	v_pk_mul_f32 v[12:13], v[12:13], v[176:177]
	v_pk_mul_f32 v[14:15], v[14:15], v[178:179]
	v_pk_mul_f32 v[16:17], v[16:17], v[180:181]
	v_pk_mul_f32 v[18:19], v[18:19], v[200:201]
	v_pk_mul_f32 v[20:21], v[20:21], v[202:203]
	v_pk_mul_f32 v[22:23], v[22:23], v[204:205]
	v_pk_mul_f32 v[24:25], v[24:25], v[206:207]
	v_pk_mul_f32 v[26:27], v[26:27], v[208:209]
	v_pk_mul_f32 v[28:29], v[28:29], v[210:211]
	v_pk_mul_f32 v[30:31], v[30:31], v[212:213]
	v_pk_mul_f32 v[32:33], v[32:33], v[214:215]
	v_cvt_pk_bf16_f32 v42, v34, v35
	v_cvt_pk_bf16_f32 v43, v36, v37
	global_store_dwordx2 v247, v[42:43], s[76:77]
	v_cvt_pk_bf16_f32 v44, v38, v39
	v_cvt_pk_bf16_f32 v45, v40, v41
	global_store_dwordx2 v247, v[44:45], s[78:79]
	s_nop 0
.Lp8_first_3:
	s_sub_i32 s48, 3, s12
	s_sub_i32 s49, 39, s12
	s_cmp_lt_u32 s12, 4
	s_cselect_b32 s48, s48, s49
	s_cmp_eq_u32 s31, 0
	s_cselect_b32 s54, s12, s48
	s_lshl_b32 s48, s54, 6
	s_add_i32 s49, s33, s48
	s_add_i32 s48, s34, s48
	s_cmp_lt_u32 s54, 4
	s_cselect_b32 s55, s49, s48
	s_add_i32 s48, s55, 16
	s_add_i32 s49, s55, 32
	s_cmp_eq_u32 s31, 0
	s_cselect_b32 s48, s48, s49
	s_lshl_b32 s48, s48, 11
	s_add_u32 s8, s28, s48
	s_addc_u32 s9, s29, 0
	s_add_i32 s48, s55, 32
	s_add_i32 s49, s55, 16
	s_cmp_eq_u32 s31, 0
	s_cselect_b32 s48, s48, s49
	s_lshl_b32 s48, s48, 11
	s_add_u32 s10, s28, s48
	s_addc_u32 s11, s29, 0
	v_cvt_pk_bf16_f32 v150, v2, v3
	v_cvt_pk_bf16_f32 v151, v4, v5
	v_cvt_pk_bf16_f32 v152, v6, v7
	v_cvt_pk_bf16_f32 v153, v8, v9
	v_cvt_pk_bf16_f32 v154, v10, v11
	v_cvt_pk_bf16_f32 v155, v12, v13
	v_cvt_pk_bf16_f32 v156, v14, v15
	v_cvt_pk_bf16_f32 v157, v16, v17
	v_cvt_pk_bf16_f32 v158, v18, v19
	v_cvt_pk_bf16_f32 v159, v20, v21
	v_cvt_pk_bf16_f32 v160, v22, v23
	v_cvt_pk_bf16_f32 v161, v24, v25
	v_cvt_pk_bf16_f32 v162, v26, v27
	v_cvt_pk_bf16_f32 v163, v28, v29
	v_cvt_pk_bf16_f32 v164, v30, v31
	v_cvt_pk_bf16_f32 v165, v32, v33
	ds_read_b64_tr_b16 v[126:127], v184 offset:35840
	ds_read_b64_tr_b16 v[128:129], v184 offset:38400
	ds_read_b64_tr_b16 v[130:131], v184 offset:40960
	ds_read_b64_tr_b16 v[132:133], v184 offset:43520
	ds_read_b64_tr_b16 v[62:63], v185 offset:17408
	ds_read_b64_tr_b16 v[64:65], v185 offset:22016
	ds_read_b64_tr_b16 v[66:67], v185 offset:26624
	ds_read_b64_tr_b16 v[68:69], v185 offset:31232
	ds_read_b64_tr_b16 v[70:71], v185 offset:17440
	ds_read_b64_tr_b16 v[72:73], v185 offset:22048
	ds_read_b64_tr_b16 v[74:75], v185 offset:26656
	ds_read_b64_tr_b16 v[76:77], v185 offset:31264
	ds_read_b64_tr_b16 v[78:79], v185 offset:17472
	ds_read_b64_tr_b16 v[80:81], v185 offset:22080
	ds_read_b64_tr_b16 v[82:83], v185 offset:26688
	ds_read_b64_tr_b16 v[84:85], v185 offset:31296
	ds_read_b64_tr_b16 v[86:87], v185 offset:17504
	ds_read_b64_tr_b16 v[88:89], v185 offset:22112
	ds_read_b64_tr_b16 v[90:91], v185 offset:26720
	ds_read_b64_tr_b16 v[92:93], v185 offset:31328
	ds_read_b64 v[94:95], v183 offset:4352
	ds_read_b64 v[96:97], v183 offset:4384
	ds_read_b64 v[98:99], v183 offset:4416
	ds_read_b64 v[100:101], v183 offset:4448
	ds_read_b64 v[102:103], v183 offset:4480
	ds_read_b64 v[104:105], v183 offset:4512
	ds_read_b64 v[106:107], v183 offset:4544
	ds_read_b64 v[108:109], v183 offset:4576
	ds_read_b64 v[110:111], v183 offset:8704
	ds_read_b64 v[112:113], v183 offset:8736
	ds_read_b64 v[114:115], v183 offset:8768
	ds_read_b64 v[116:117], v183 offset:8800
	ds_read_b64 v[118:119], v183 offset:8832
	ds_read_b64 v[120:121], v183 offset:8864
	ds_read_b64 v[122:123], v183 offset:8896
	ds_read_b64 v[124:125], v183 offset:8928
	s_barrier
	s_waitcnt lgkmcnt(15)
	v_mfma_f32_16x16x32_bf16 v[2:5], v[62:65], v[126:129], v[2:5]
	v_mfma_f32_16x16x32_bf16 v[2:5], v[66:69], v[130:133], v[2:5]
	v_mfma_f32_16x16x32_bf16 v[6:9], v[70:73], v[126:129], v[6:9]
	v_mfma_f32_16x16x32_bf16 v[6:9], v[74:77], v[130:133], v[6:9]
	v_mfma_f32_16x16x32_bf16 v[10:13], v[78:81], v[126:129], v[10:13]
	v_mfma_f32_16x16x32_bf16 v[10:13], v[82:85], v[130:133], v[10:13]
	v_mfma_f32_16x16x32_bf16 v[14:17], v[86:89], v[126:129], v[14:17]
	v_mfma_f32_16x16x32_bf16 v[14:17], v[90:93], v[130:133], v[14:17]
	s_waitcnt lgkmcnt(0)
	v_mfma_f32_16x16x32_bf16 v[34:37], v[150:153], v[94:97], 0
	v_mfma_f32_16x16x32_bf16 v[38:41], v[150:153], v[110:113], 0
	v_mfma_f32_16x16x32_bf16 v[34:37], v[154:157], v[98:101], v[34:37]
	v_mfma_f32_16x16x32_bf16 v[38:41], v[154:157], v[114:117], v[38:41]
	v_mfma_f32_16x16x32_bf16 v[34:37], v[158:161], v[102:105], v[34:37]
	v_mfma_f32_16x16x32_bf16 v[38:41], v[158:161], v[118:121], v[38:41]
	v_mfma_f32_16x16x32_bf16 v[34:37], v[162:165], v[106:109], v[34:37]
	v_mfma_f32_16x16x32_bf16 v[38:41], v[162:165], v[122:125], v[38:41]
	ds_read_b128 v[62:65], v182 offset:4352
	ds_read_b128 v[66:69], v182 offset:4416
	ds_read_b128 v[70:73], v182 offset:4480
	ds_read_b128 v[74:77], v182 offset:4544
	ds_read_b128 v[78:81], v182 offset:8704
	ds_read_b128 v[82:85], v182 offset:8768
	ds_read_b128 v[86:89], v182 offset:8832
	ds_read_b128 v[90:93], v182 offset:8896
	ds_read_b128 v[166:169], v242 offset:17408
	ds_read_b128 v[170:173], v242 offset:17472
	ds_read_b128 v[174:177], v242 offset:17536
	ds_read_b128 v[178:181], v242 offset:17600
	ds_read_b128 v[200:203], v242 offset:22016
	ds_read_b128 v[204:207], v242 offset:22080
	ds_read_b128 v[208:211], v242 offset:22144
	ds_read_b128 v[212:215], v242 offset:22208
	ds_read_b128 v[94:97], v242 offset:26624
	ds_read_b128 v[98:101], v242 offset:26688
	ds_read_b128 v[102:105], v242 offset:26752
	ds_read_b128 v[106:109], v242 offset:26816
	s_cmp_gt_u32 s12, 5
	s_cbranch_scc1 .Lp8_w10_4
	s_waitcnt vmcnt(6)
	s_branch .Lp8_wd_4

.Lp8_wd_4:
	ds_write_b128 v243, v[142:145] offset:17408
	ds_write_b128 v243, v[146:149] offset:26624
	ds_write_b128 v190, v[238:241] offset:35840
	ds_write_b128 v189, v[134:137]
	ds_write_b128 v189, v[138:141] offset:8704
	ds_write_b32 v191, v237
	s_add_i32 s64, s12, 3
	s_min_u32 s65, s64, 35
	s_sub_i32 s48, 3, s65
	s_sub_i32 s49, 39, s65
	s_cmp_lt_u32 s65, 4
	s_cselect_b32 s48, s48, s49
	s_cmp_eq_u32 s31, 0
	s_cselect_b32 s54, s65, s48
	s_lshl_b32 s48, s54, 6
	s_add_i32 s49, s33, s48
	s_add_i32 s48, s34, s48
	s_cmp_lt_u32 s54, 4
	s_cselect_b32 s55, s49, s48
	s_mul_i32 s48, s55, s30
	s_add_u32 s0, s16, s48
	s_addc_u32 s1, s17, 0
	s_add_u32 s2, s18, s48
	s_addc_u32 s3, s19, 0
	s_mul_i32 s48, s55, 0x1800
	s_add_u32 s4, s20, s48
	s_addc_u32 s5, s21, 0
	s_lshl_b32 s48, s54, 9
	s_add_u32 s6, s22, s48
	s_addc_u32 s7, s23, 0
	global_load_dwordx4 v[142:145], v244, s[2:3]
	global_load_dwordx4 v[146:149], v245, s[2:3]
	global_load_dwordx4 v[238:241], v246, s[4:5]
	global_load_dwordx4 v[134:137], v244, s[0:1]
	global_load_dwordx4 v[138:141], v245, s[0:1]
	global_load_dword v237, v194, s[6:7]
	s_barrier
	s_waitcnt lgkmcnt(14)
	v_mfma_f32_16x16x32_bf16 v[42:45], v[166:169], v[62:65], 0
	v_mfma_f32_16x16x32_bf16 v[50:53], v[166:169], v[78:81], 0
	v_mfma_f32_16x16x32_bf16 v[42:45], v[170:173], v[66:69], v[42:45]
	v_mfma_f32_16x16x32_bf16 v[50:53], v[170:173], v[82:85], v[50:53]
	v_mfma_f32_16x16x32_bf16 v[42:45], v[174:177], v[70:73], v[42:45]
	v_mfma_f32_16x16x32_bf16 v[50:53], v[174:177], v[86:89], v[50:53]
	v_mfma_f32_16x16x32_bf16 v[42:45], v[178:181], v[74:77], v[42:45]
	v_mfma_f32_16x16x32_bf16 v[50:53], v[178:181], v[90:93], v[50:53]
	s_waitcnt lgkmcnt(10)
	v_mfma_f32_16x16x32_bf16 v[46:49], v[200:203], v[62:65], 0
	v_mfma_f32_16x16x32_bf16 v[54:57], v[200:203], v[78:81], 0
	v_mfma_f32_16x16x32_bf16 v[46:49], v[204:207], v[66:69], v[46:49]
	v_mfma_f32_16x16x32_bf16 v[54:57], v[204:207], v[82:85], v[54:57]
	v_mfma_f32_16x16x32_bf16 v[46:49], v[208:211], v[70:73], v[46:49]
	v_mfma_f32_16x16x32_bf16 v[54:57], v[208:211], v[86:89], v[54:57]
	v_mfma_f32_16x16x32_bf16 v[46:49], v[212:215], v[74:77], v[46:49]
	v_mfma_f32_16x16x32_bf16 v[54:57], v[212:215], v[90:93], v[54:57]
	s_waitcnt lgkmcnt(6)
	v_mfma_f32_16x16x32_bf16 v[58:61], v[94:97], v[78:81], 0
	v_mfma_f32_16x16x32_bf16 v[58:61], v[98:101], v[82:85], v[58:61]
	v_mfma_f32_16x16x32_bf16 v[58:61], v[102:105], v[86:89], v[58:61]
	v_mfma_f32_16x16x32_bf16 v[58:61], v[106:109], v[90:93], v[58:61]
	ds_read_b64_tr_b16 v[62:63], v185 offset:17536
	ds_read_b64_tr_b16 v[64:65], v185 offset:22144
	ds_read_b64_tr_b16 v[66:67], v185 offset:26752
	ds_read_b64_tr_b16 v[68:69], v185 offset:31360
	ds_read_b64_tr_b16 v[70:71], v185 offset:17568
	ds_read_b64_tr_b16 v[72:73], v185 offset:22176
	ds_read_b64_tr_b16 v[74:75], v185 offset:26784
	ds_read_b64_tr_b16 v[76:77], v185 offset:31392
	ds_read_b64_tr_b16 v[78:79], v185 offset:17600
	ds_read_b64_tr_b16 v[80:81], v185 offset:22208
	ds_read_b64_tr_b16 v[82:83], v185 offset:26816
	ds_read_b64_tr_b16 v[84:85], v185 offset:31424
	ds_read_b64_tr_b16 v[86:87], v185 offset:17632
	ds_read_b64_tr_b16 v[88:89], v185 offset:22240
	ds_read_b64_tr_b16 v[90:91], v185 offset:26848
	ds_read_b64_tr_b16 v[92:93], v185 offset:31456
	ds_read_b128 v[166:169], v188 offset:0
	ds_read_b128 v[170:173], v188 offset:64
	ds_read_b128 v[174:177], v188 offset:128
	ds_read_b128 v[178:181], v188 offset:192
	ds_read_b128 v[200:203], v188 offset:256
	ds_read_b128 v[204:207], v188 offset:320
	ds_read_b128 v[208:211], v188 offset:384
	ds_read_b128 v[212:215], v188 offset:448
	s_mov_b64 s[76:77], s[8:9]
	s_mov_b64 s[78:79], s[10:11]
	s_waitcnt lgkmcnt(15)
	s_barrier
.Lp8_next_0:
	s_add_i32 s12, s12, 1
	v_add_u32_e32 v182, 0xb400, v182
	v_add_u32_e32 v183, 0xb400, v183
	v_add_u32_e32 v184, 0xb400, v184
	v_add_u32_e32 v185, 0xb400, v185
	v_add_u32_e32 v242, 0xb400, v242
	v_add_u32_e32 v189, 0xffff4c00, v189
	v_add_u32_e32 v243, 0xffff4c00, v243
	v_add_u32_e32 v190, 0xffff4c00, v190
	v_add_u32_e32 v188, 0x200, v188
	v_add_u32_e32 v191, 0xfffffe00, v191
	s_cmp_lt_u32 s12, 4
	s_nop 0
	s_cbranch_scc0 .Lp8_lat_1
	ds_read_b64_tr_b16 v[126:127], v184 offset:35840
	ds_read_b64_tr_b16 v[128:129], v184 offset:38400
	ds_read_b64_tr_b16 v[130:131], v184 offset:40960
	ds_read_b64_tr_b16 v[132:133], v184 offset:43520
	ds_read_b64_tr_b16 v[62:63], v185 offset:17408
	ds_read_b64_tr_b16 v[64:65], v185 offset:22016
	ds_read_b64_tr_b16 v[66:67], v185 offset:26624
	ds_read_b64_tr_b16 v[68:69], v185 offset:31232
	ds_read_b64_tr_b16 v[70:71], v185 offset:17440
	ds_read_b64_tr_b16 v[72:73], v185 offset:22048
	ds_read_b64_tr_b16 v[74:75], v185 offset:26656
	ds_read_b64_tr_b16 v[76:77], v185 offset:31264
	ds_read_b64_tr_b16 v[78:79], v185 offset:17472
	ds_read_b64_tr_b16 v[80:81], v185 offset:22080
	ds_read_b64_tr_b16 v[82:83], v185 offset:26688
	ds_read_b64_tr_b16 v[84:85], v185 offset:31296
	ds_read_b64_tr_b16 v[86:87], v185 offset:17504
	ds_read_b64_tr_b16 v[88:89], v185 offset:22112
	ds_read_b64_tr_b16 v[90:91], v185 offset:26720
	ds_read_b64_tr_b16 v[92:93], v185 offset:31328
	ds_read_b64_tr_b16 v[94:95], v185 offset:17536
	ds_read_b64_tr_b16 v[96:97], v185 offset:22144
	ds_read_b64_tr_b16 v[98:99], v185 offset:26752
	ds_read_b64_tr_b16 v[100:101], v185 offset:31360
	ds_read_b64_tr_b16 v[102:103], v185 offset:17568
	ds_read_b64_tr_b16 v[104:105], v185 offset:22176
	ds_read_b64_tr_b16 v[106:107], v185 offset:26784
	ds_read_b64_tr_b16 v[108:109], v185 offset:31392
	ds_read_b64_tr_b16 v[110:111], v185 offset:17600
	ds_read_b64_tr_b16 v[112:113], v185 offset:22208
	ds_read_b64_tr_b16 v[114:115], v185 offset:26816
	ds_read_b64_tr_b16 v[116:117], v185 offset:31424
	ds_read_b64_tr_b16 v[118:119], v185 offset:17632
	ds_read_b64_tr_b16 v[120:121], v185 offset:22240
	ds_read_b64_tr_b16 v[122:123], v185 offset:26848
	ds_read_b64_tr_b16 v[124:125], v185 offset:31456
	ds_read_b128 v[166:169], v188 offset:0
	ds_read_b128 v[170:173], v188 offset:64
	ds_read_b128 v[174:177], v188 offset:128
	ds_read_b128 v[178:181], v188 offset:192
	ds_read_b128 v[200:203], v188 offset:256
	ds_read_b128 v[204:207], v188 offset:320
	ds_read_b128 v[208:211], v188 offset:384
	ds_read_b128 v[212:215], v188 offset:448
	s_waitcnt vmcnt(6)
	ds_write_b128 v243, v[224:227] offset:17408
	ds_write_b128 v243, v[228:231] offset:26624
	ds_write_b128 v190, v[232:235] offset:35840
	ds_write_b128 v189, v[216:219]
	ds_write_b128 v189, v[220:223] offset:8704
	ds_write_b32 v191, v236
	s_add_i32 s64, s12, 3
	s_min_u32 s65, s64, 35
	s_sub_i32 s48, 3, s65
	s_sub_i32 s49, 39, s65
	s_cmp_lt_u32 s65, 4
	s_cselect_b32 s48, s48, s49
	s_cmp_eq_u32 s31, 0
	s_cselect_b32 s54, s65, s48
	s_lshl_b32 s48, s54, 6
	s_add_i32 s49, s33, s48
	s_add_i32 s48, s34, s48
	s_cmp_lt_u32 s54, 4
	s_cselect_b32 s55, s49, s48
	s_mul_i32 s48, s55, s30
	s_add_u32 s0, s16, s48
	s_addc_u32 s1, s17, 0
	s_add_u32 s2, s18, s48
	s_addc_u32 s3, s19, 0
	s_mul_i32 s48, s55, 0x1800
	s_add_u32 s4, s20, s48
	s_addc_u32 s5, s21, 0
	s_lshl_b32 s48, s54, 9
	s_add_u32 s6, s22, s48
	s_addc_u32 s7, s23, 0
	global_load_dwordx4 v[224:227], v244, s[2:3]
	global_load_dwordx4 v[228:231], v245, s[2:3]
	global_load_dwordx4 v[232:235], v246, s[4:5]
	global_load_dwordx4 v[216:219], v244, s[0:1]
	global_load_dwordx4 v[220:223], v245, s[0:1]
	global_load_dword v236, v194, s[6:7]
	s_waitcnt lgkmcnt(15)
	v_mfma_f32_16x16x32_bf16 v[2:5], v[62:65], v[126:129], v[2:5]
	v_mfma_f32_16x16x32_bf16 v[2:5], v[66:69], v[130:133], v[2:5]
	v_mfma_f32_16x16x32_bf16 v[6:9], v[70:73], v[126:129], v[6:9]
	v_mfma_f32_16x16x32_bf16 v[6:9], v[74:77], v[130:133], v[6:9]
	v_mfma_f32_16x16x32_bf16 v[10:13], v[78:81], v[126:129], v[10:13]
	v_mfma_f32_16x16x32_bf16 v[10:13], v[82:85], v[130:133], v[10:13]
	v_mfma_f32_16x16x32_bf16 v[14:17], v[86:89], v[126:129], v[14:17]
	v_mfma_f32_16x16x32_bf16 v[14:17], v[90:93], v[130:133], v[14:17]
	s_waitcnt lgkmcnt(14)
	v_mfma_f32_16x16x32_bf16 v[18:21], v[94:97], v[126:129], v[18:21]
	v_mfma_f32_16x16x32_bf16 v[18:21], v[98:101], v[130:133], v[18:21]
	v_mfma_f32_16x16x32_bf16 v[22:25], v[102:105], v[126:129], v[22:25]
	v_mfma_f32_16x16x32_bf16 v[22:25], v[106:109], v[130:133], v[22:25]
	v_mfma_f32_16x16x32_bf16 v[26:29], v[110:113], v[126:129], v[26:29]
	v_mfma_f32_16x16x32_bf16 v[26:29], v[114:117], v[130:133], v[26:29]
	v_mfma_f32_16x16x32_bf16 v[30:33], v[118:121], v[126:129], v[30:33]
	v_mfma_f32_16x16x32_bf16 v[30:33], v[122:125], v[130:133], v[30:33]
	s_waitcnt lgkmcnt(0)
	v_pk_mul_f32 v[2:3], v[2:3], v[166:167]
	v_pk_mul_f32 v[4:5], v[4:5], v[168:169]
	v_pk_mul_f32 v[6:7], v[6:7], v[170:171]
	v_pk_mul_f32 v[8:9], v[8:9], v[172:173]
	v_pk_mul_f32 v[10:11], v[10:11], v[174:175]
	v_pk_mul_f32 v[12:13], v[12:13], v[176:177]
	v_pk_mul_f32 v[14:15], v[14:15], v[178:179]
	v_pk_mul_f32 v[16:17], v[16:17], v[180:181]
	v_pk_mul_f32 v[18:19], v[18:19], v[200:201]
	v_pk_mul_f32 v[20:21], v[20:21], v[202:203]
	v_pk_mul_f32 v[22:23], v[22:23], v[204:205]
	v_pk_mul_f32 v[24:25], v[24:25], v[206:207]
	v_pk_mul_f32 v[26:27], v[26:27], v[208:209]
	v_pk_mul_f32 v[28:29], v[28:29], v[210:211]
	v_pk_mul_f32 v[30:31], v[30:31], v[212:213]
	v_pk_mul_f32 v[32:33], v[32:33], v[214:215]
	s_nop 1
	s_barrier
	s_branch .Lp8_next_1

.Lp8_wd_6:
	ds_write_b128 v243, v[224:227] offset:17408
	ds_write_b128 v243, v[228:231] offset:26624
	ds_write_b128 v190, v[232:235] offset:35840
	ds_write_b128 v189, v[216:219]
	ds_write_b128 v189, v[220:223] offset:8704
	ds_write_b32 v191, v236
	s_add_i32 s64, s12, 3
	s_min_u32 s65, s64, 35
	s_sub_i32 s48, 3, s65
	s_sub_i32 s49, 39, s65
	s_cmp_lt_u32 s65, 4
	s_cselect_b32 s48, s48, s49
	s_cmp_eq_u32 s31, 0
	s_cselect_b32 s54, s65, s48
	s_lshl_b32 s48, s54, 6
	s_add_i32 s49, s33, s48
	s_add_i32 s48, s34, s48
	s_cmp_lt_u32 s54, 4
	s_cselect_b32 s55, s49, s48
	s_mul_i32 s48, s55, s30
	s_add_u32 s0, s16, s48
	s_addc_u32 s1, s17, 0
	s_add_u32 s2, s18, s48
	s_addc_u32 s3, s19, 0
	s_mul_i32 s48, s55, 0x1800
	s_add_u32 s4, s20, s48
	s_addc_u32 s5, s21, 0
	s_lshl_b32 s48, s54, 9
	s_add_u32 s6, s22, s48
	s_addc_u32 s7, s23, 0
	global_load_dwordx4 v[224:227], v244, s[2:3]
	global_load_dwordx4 v[228:231], v245, s[2:3]
	global_load_dwordx4 v[232:235], v246, s[4:5]
	global_load_dwordx4 v[216:219], v244, s[0:1]
	global_load_dwordx4 v[220:223], v245, s[0:1]
	global_load_dword v236, v194, s[6:7]
	s_waitcnt lgkmcnt(15)
	v_mfma_f32_16x16x32_bf16 v[42:45], v[166:169], v[62:65], 0
	v_mfma_f32_16x16x32_bf16 v[46:49], v[166:169], v[78:81], 0
	v_mfma_f32_16x16x32_bf16 v[42:45], v[170:173], v[66:69], v[42:45]
	v_mfma_f32_16x16x32_bf16 v[46:49], v[170:173], v[82:85], v[46:49]
	v_mfma_f32_16x16x32_bf16 v[42:45], v[174:177], v[70:73], v[42:45]
	v_mfma_f32_16x16x32_bf16 v[46:49], v[174:177], v[86:89], v[46:49]
	v_mfma_f32_16x16x32_bf16 v[42:45], v[178:181], v[74:77], v[42:45]
	v_mfma_f32_16x16x32_bf16 v[46:49], v[178:181], v[90:93], v[46:49]
	s_waitcnt lgkmcnt(14)
	v_mfma_f32_16x16x32_bf16 v[50:53], v[200:203], v[78:81], 0
	v_mfma_f32_16x16x32_bf16 v[50:53], v[204:207], v[82:85], v[50:53]
	v_mfma_f32_16x16x32_bf16 v[50:53], v[208:211], v[86:89], v[50:53]
	v_mfma_f32_16x16x32_bf16 v[50:53], v[212:215], v[90:93], v[50:53]
	s_waitcnt lgkmcnt(10)
	v_mfma_f32_16x16x32_bf16 v[54:57], v[94:97], v[78:81], 0
	v_mfma_f32_16x16x32_bf16 v[54:57], v[98:101], v[82:85], v[54:57]
	v_mfma_f32_16x16x32_bf16 v[54:57], v[102:105], v[86:89], v[54:57]
	v_mfma_f32_16x16x32_bf16 v[54:57], v[106:109], v[90:93], v[54:57]
	s_waitcnt lgkmcnt(6)
	v_mfma_f32_16x16x32_bf16 v[58:61], v[110:113], v[78:81], 0
	v_mfma_f32_16x16x32_bf16 v[58:61], v[114:117], v[82:85], v[58:61]
	v_mfma_f32_16x16x32_bf16 v[58:61], v[118:121], v[86:89], v[58:61]
	v_mfma_f32_16x16x32_bf16 v[58:61], v[122:125], v[90:93], v[58:61]
	s_nop 7
	s_barrier
	ds_read_b64_tr_b16 v[62:63], v185 offset:17536
	ds_read_b64_tr_b16 v[64:65], v185 offset:22144
	ds_read_b64_tr_b16 v[66:67], v185 offset:26752
	ds_read_b64_tr_b16 v[68:69], v185 offset:31360
	ds_read_b64_tr_b16 v[70:71], v185 offset:17568
	ds_read_b64_tr_b16 v[72:73], v185 offset:22176
	ds_read_b64_tr_b16 v[74:75], v185 offset:26784
	ds_read_b64_tr_b16 v[76:77], v185 offset:31392
	ds_read_b64_tr_b16 v[78:79], v185 offset:17600
	ds_read_b64_tr_b16 v[80:81], v185 offset:22208
	ds_read_b64_tr_b16 v[82:83], v185 offset:26816
	ds_read_b64_tr_b16 v[84:85], v185 offset:31424
	ds_read_b64_tr_b16 v[86:87], v185 offset:17632
	ds_read_b64_tr_b16 v[88:89], v185 offset:22240
	ds_read_b64_tr_b16 v[90:91], v185 offset:26848
	ds_read_b64_tr_b16 v[92:93], v185 offset:31456
	ds_read_b128 v[166:169], v188 offset:0
	ds_read_b128 v[170:173], v188 offset:64
	ds_read_b128 v[174:177], v188 offset:128
	ds_read_b128 v[178:181], v188 offset:192
	ds_read_b128 v[200:203], v188 offset:256
	ds_read_b128 v[204:207], v188 offset:320
	ds_read_b128 v[208:211], v188 offset:384
	ds_read_b128 v[212:215], v188 offset:448
	s_waitcnt lgkmcnt(8)
	v_mfma_f32_16x16x32_bf16 v[18:21], v[62:65], v[126:129], v[18:21]
	v_mfma_f32_16x16x32_bf16 v[18:21], v[66:69], v[130:133], v[18:21]
	v_mfma_f32_16x16x32_bf16 v[22:25], v[70:73], v[126:129], v[22:25]
	v_mfma_f32_16x16x32_bf16 v[22:25], v[74:77], v[130:133], v[22:25]
	v_mfma_f32_16x16x32_bf16 v[26:29], v[78:81], v[126:129], v[26:29]
	v_mfma_f32_16x16x32_bf16 v[26:29], v[82:85], v[130:133], v[26:29]
	v_mfma_f32_16x16x32_bf16 v[30:33], v[86:89], v[126:129], v[30:33]
	v_mfma_f32_16x16x32_bf16 v[30:33], v[90:93], v[130:133], v[30:33]
	v_cndmask_b32_e64 v42, v42, 0, s[40:41]
	v_cndmask_b32_e64 v43, v43, 0, s[42:43]
	v_cndmask_b32_e64 v44, v44, 0, s[44:45]
	v_cndmask_b32_e64 v45, v45, 0, s[46:47]
	v_cndmask_b32_e64 v58, v58, 0, s[40:41]
	v_cndmask_b32_e64 v59, v59, 0, s[42:43]
	v_cndmask_b32_e64 v60, v60, 0, s[44:45]
	v_cndmask_b32_e64 v61, v61, 0, s[46:47]
	v_cvt_pk_bf16_f32 v150, v42, v43
	v_cvt_pk_bf16_f32 v151, v44, v45
	v_mov_b32_e32 v152, 0
	v_mov_b32_e32 v153, 0
	v_cvt_pk_bf16_f32 v154, v46, v47
	v_cvt_pk_bf16_f32 v155, v48, v49
	v_cvt_pk_bf16_f32 v156, v50, v51
	v_cvt_pk_bf16_f32 v157, v52, v53
	v_cvt_pk_bf16_f32 v158, v54, v55
	v_cvt_pk_bf16_f32 v159, v56, v57
	v_cvt_pk_bf16_f32 v160, v58, v59
	v_cvt_pk_bf16_f32 v161, v60, v61
	v_mfma_f32_16x16x32_bf16 v[34:37], v[126:129], v[150:153], v[34:37]
	v_mfma_f32_16x16x32_bf16 v[38:41], v[126:129], v[154:157], v[38:41]
	v_mfma_f32_16x16x32_bf16 v[38:41], v[130:133], v[158:161], v[38:41]
	s_waitcnt lgkmcnt(0)
	v_pk_mul_f32 v[2:3], v[2:3], v[166:167]
	v_pk_mul_f32 v[4:5], v[4:5], v[168:169]
	v_pk_mul_f32 v[6:7], v[6:7], v[170:171]
	v_pk_mul_f32 v[8:9], v[8:9], v[172:173]
	v_pk_mul_f32 v[10:11], v[10:11], v[174:175]
	v_pk_mul_f32 v[12:13], v[12:13], v[176:177]
	v_pk_mul_f32 v[14:15], v[14:15], v[178:179]
	v_pk_mul_f32 v[16:17], v[16:17], v[180:181]
	v_pk_mul_f32 v[18:19], v[18:19], v[200:201]
	v_pk_mul_f32 v[20:21], v[20:21], v[202:203]
	v_pk_mul_f32 v[22:23], v[22:23], v[204:205]
	v_pk_mul_f32 v[24:25], v[24:25], v[206:207]
	v_pk_mul_f32 v[26:27], v[26:27], v[208:209]
	v_pk_mul_f32 v[28:29], v[28:29], v[210:211]
	v_pk_mul_f32 v[30:31], v[30:31], v[212:213]
	v_pk_mul_f32 v[32:33], v[32:33], v[214:215]
	v_cvt_pk_bf16_f32 v42, v34, v35
	v_cvt_pk_bf16_f32 v43, v36, v37
	global_store_dwordx2 v247, v[42:43], s[8:9]
	v_cvt_pk_bf16_f32 v44, v38, v39
	v_cvt_pk_bf16_f32 v45, v40, v41
	global_store_dwordx2 v247, v[44:45], s[10:11]
	s_nop 0
	s_barrier
	s_branch .Lp8_next_1

.Lp8_wd_8:
	ds_write_b128 v243, v[224:227] offset:17408
	ds_write_b128 v243, v[228:231] offset:26624
	ds_write_b128 v190, v[232:235] offset:35840
	ds_write_b128 v189, v[216:219]
	ds_write_b128 v189, v[220:223] offset:8704
	ds_write_b32 v191, v236
	s_add_i32 s64, s12, 3
	s_min_u32 s65, s64, 35
	s_sub_i32 s48, 3, s65
	s_sub_i32 s49, 39, s65
	s_cmp_lt_u32 s65, 4
	s_cselect_b32 s48, s48, s49
	s_cmp_eq_u32 s31, 0
	s_cselect_b32 s54, s65, s48
	s_lshl_b32 s48, s54, 6
	s_add_i32 s49, s33, s48
	s_add_i32 s48, s34, s48
	s_cmp_lt_u32 s54, 4
	s_cselect_b32 s55, s49, s48
	s_mul_i32 s48, s55, s30
	s_add_u32 s0, s16, s48
	s_addc_u32 s1, s17, 0
	s_add_u32 s2, s18, s48
	s_addc_u32 s3, s19, 0
	s_mul_i32 s48, s55, 0x1800
	s_add_u32 s4, s20, s48
	s_addc_u32 s5, s21, 0
	s_lshl_b32 s48, s54, 9
	s_add_u32 s6, s22, s48
	s_addc_u32 s7, s23, 0
	global_load_dwordx4 v[224:227], v244, s[2:3]
	global_load_dwordx4 v[228:231], v245, s[2:3]
	global_load_dwordx4 v[232:235], v246, s[4:5]
	global_load_dwordx4 v[216:219], v244, s[0:1]
	global_load_dwordx4 v[220:223], v245, s[0:1]
	global_load_dword v236, v194, s[6:7]
	s_barrier
	s_waitcnt lgkmcnt(14)
	v_mfma_f32_16x16x32_bf16 v[42:45], v[166:169], v[62:65], 0
	v_mfma_f32_16x16x32_bf16 v[50:53], v[166:169], v[78:81], 0
	v_mfma_f32_16x16x32_bf16 v[42:45], v[170:173], v[66:69], v[42:45]
	v_mfma_f32_16x16x32_bf16 v[50:53], v[170:173], v[82:85], v[50:53]
	v_mfma_f32_16x16x32_bf16 v[42:45], v[174:177], v[70:73], v[42:45]
	v_mfma_f32_16x16x32_bf16 v[50:53], v[174:177], v[86:89], v[50:53]
	v_mfma_f32_16x16x32_bf16 v[42:45], v[178:181], v[74:77], v[42:45]
	v_mfma_f32_16x16x32_bf16 v[50:53], v[178:181], v[90:93], v[50:53]
	s_waitcnt lgkmcnt(10)
	v_mfma_f32_16x16x32_bf16 v[46:49], v[200:203], v[62:65], 0
	v_mfma_f32_16x16x32_bf16 v[54:57], v[200:203], v[78:81], 0
	v_mfma_f32_16x16x32_bf16 v[46:49], v[204:207], v[66:69], v[46:49]
	v_mfma_f32_16x16x32_bf16 v[54:57], v[204:207], v[82:85], v[54:57]
	v_mfma_f32_16x16x32_bf16 v[46:49], v[208:211], v[70:73], v[46:49]
	v_mfma_f32_16x16x32_bf16 v[54:57], v[208:211], v[86:89], v[54:57]
	v_mfma_f32_16x16x32_bf16 v[46:49], v[212:215], v[74:77], v[46:49]
	v_mfma_f32_16x16x32_bf16 v[54:57], v[212:215], v[90:93], v[54:57]
	s_waitcnt lgkmcnt(6)
	v_mfma_f32_16x16x32_bf16 v[58:61], v[94:97], v[78:81], 0
	v_mfma_f32_16x16x32_bf16 v[58:61], v[98:101], v[82:85], v[58:61]
	v_mfma_f32_16x16x32_bf16 v[58:61], v[102:105], v[86:89], v[58:61]
	v_mfma_f32_16x16x32_bf16 v[58:61], v[106:109], v[90:93], v[58:61]
	ds_read_b64_tr_b16 v[62:63], v185 offset:17536
	ds_read_b64_tr_b16 v[64:65], v185 offset:22144
	ds_read_b64_tr_b16 v[66:67], v185 offset:26752
	ds_read_b64_tr_b16 v[68:69], v185 offset:31360
	ds_read_b64_tr_b16 v[70:71], v185 offset:17568
	ds_read_b64_tr_b16 v[72:73], v185 offset:22176
	ds_read_b64_tr_b16 v[74:75], v185 offset:26784
	ds_read_b64_tr_b16 v[76:77], v185 offset:31392
	ds_read_b64_tr_b16 v[78:79], v185 offset:17600
	ds_read_b64_tr_b16 v[80:81], v185 offset:22208
	ds_read_b64_tr_b16 v[82:83], v185 offset:26816
	ds_read_b64_tr_b16 v[84:85], v185 offset:31424
	ds_read_b64_tr_b16 v[86:87], v185 offset:17632
	ds_read_b64_tr_b16 v[88:89], v185 offset:22240
	ds_read_b64_tr_b16 v[90:91], v185 offset:26848
	ds_read_b64_tr_b16 v[92:93], v185 offset:31456
	ds_read_b128 v[166:169], v188 offset:0
	ds_read_b128 v[170:173], v188 offset:64
	ds_read_b128 v[174:177], v188 offset:128
	ds_read_b128 v[178:181], v188 offset:192
	ds_read_b128 v[200:203], v188 offset:256
	ds_read_b128 v[204:207], v188 offset:320
	ds_read_b128 v[208:211], v188 offset:384
	ds_read_b128 v[212:215], v188 offset:448
	s_mov_b64 s[76:77], s[8:9]
	s_mov_b64 s[78:79], s[10:11]
	s_waitcnt lgkmcnt(15)
	s_barrier
.Lp8_next_1:
	s_add_i32 s12, s12, 1
	s_cmp_lt_u32 s12, 36
	s_cbranch_scc1 .Lp8_step
	s_cmp_eq_u32 s37, 0
	s_cbranch_scc1 .Lp8_done
	s_waitcnt lgkmcnt(8)
	v_mfma_f32_16x16x32_bf16 v[18:21], v[62:65], v[126:129], v[18:21]
	v_mfma_f32_16x16x32_bf16 v[18:21], v[66:69], v[130:133], v[18:21]
	v_mfma_f32_16x16x32_bf16 v[22:25], v[70:73], v[126:129], v[22:25]
	v_mfma_f32_16x16x32_bf16 v[22:25], v[74:77], v[130:133], v[22:25]
	v_mfma_f32_16x16x32_bf16 v[26:29], v[78:81], v[126:129], v[26:29]
	v_mfma_f32_16x16x32_bf16 v[26:29], v[82:85], v[130:133], v[26:29]
	v_mfma_f32_16x16x32_bf16 v[30:33], v[86:89], v[126:129], v[30:33]
	v_mfma_f32_16x16x32_bf16 v[30:33], v[90:93], v[130:133], v[30:33]
	v_cndmask_b32_e64 v46, v46, 0, s[40:41]
	v_cndmask_b32_e64 v47, v47, 0, s[42:43]
	v_cndmask_b32_e64 v48, v48, 0, s[44:45]
	v_cndmask_b32_e64 v49, v49, 0, s[46:47]
	v_cndmask_b32_e64 v58, v58, 0, s[40:41]
	v_cndmask_b32_e64 v59, v59, 0, s[42:43]
	v_cndmask_b32_e64 v60, v60, 0, s[44:45]
	v_cndmask_b32_e64 v61, v61, 0, s[46:47]
	v_cvt_pk_bf16_f32 v150, v42, v43
	v_cvt_pk_bf16_f32 v151, v44, v45
	v_cvt_pk_bf16_f32 v152, v46, v47
	v_cvt_pk_bf16_f32 v153, v48, v49
	v_cvt_pk_bf16_f32 v154, v50, v51
	v_cvt_pk_bf16_f32 v155, v52, v53
	v_cvt_pk_bf16_f32 v156, v54, v55
	v_cvt_pk_bf16_f32 v157, v56, v57
	v_cvt_pk_bf16_f32 v158, v58, v59
	v_cvt_pk_bf16_f32 v159, v60, v61
	v_mov_b32_e32 v160, 0
	v_mov_b32_e32 v161, 0
	v_mfma_f32_16x16x32_bf16 v[34:37], v[126:129], v[150:153], v[34:37]
	v_mfma_f32_16x16x32_bf16 v[38:41], v[126:129], v[154:157], v[38:41]
	v_mfma_f32_16x16x32_bf16 v[38:41], v[130:133], v[158:161], v[38:41]
	s_waitcnt lgkmcnt(0)
	v_pk_mul_f32 v[2:3], v[2:3], v[166:167]
	v_pk_mul_f32 v[4:5], v[4:5], v[168:169]
	v_pk_mul_f32 v[6:7], v[6:7], v[170:171]
	v_pk_mul_f32 v[8:9], v[8:9], v[172:173]
	v_pk_mul_f32 v[10:11], v[10:11], v[174:175]
	v_pk_mul_f32 v[12:13], v[12:13], v[176:177]
	v_pk_mul_f32 v[14:15], v[14:15], v[178:179]
	v_pk_mul_f32 v[16:17], v[16:17], v[180:181]
	v_pk_mul_f32 v[18:19], v[18:19], v[200:201]
	v_pk_mul_f32 v[20:21], v[20:21], v[202:203]
	v_pk_mul_f32 v[22:23], v[22:23], v[204:205]
	v_pk_mul_f32 v[24:25], v[24:25], v[206:207]
	v_pk_mul_f32 v[26:27], v[26:27], v[208:209]
	v_pk_mul_f32 v[28:29], v[28:29], v[210:211]
	v_pk_mul_f32 v[30:31], v[30:31], v[212:213]
	v_pk_mul_f32 v[32:33], v[32:33], v[214:215]
	v_cvt_pk_bf16_f32 v42, v34, v35
	v_cvt_pk_bf16_f32 v43, v36, v37
	global_store_dwordx2 v247, v[42:43], s[76:77]
	v_cvt_pk_bf16_f32 v44, v38, v39
	v_cvt_pk_bf16_f32 v45, v40, v41
	global_store_dwordx2 v247, v[44:45], s[78:79]
	s_nop 0
.Lp8_done:
	s_branch .LBB0_997
